# peel+rstdpf version + counted waits: compiler-inserted s_waitcnt vmcnt(0) in the in-proj K-loop SP1 load segment removed (the protocol's vmcnt(8) waits cover every LDS-DMA piece, as in the out-proj lo
# baseline (speedup 1.0000x reference)
; #define PG8_STAGE(bufoff, gbase, voff) do { _Pragma("unroll") for (int _i = 0; _i < 2; ++_i) \
;         __builtin_amdgcn_global_load_lds((const unsigned*)((const char*)(gbase) + (voff)[_i]), (PG8_LAS unsigned*)(lds + (bufoff) + ldsw + _i * 8192), 16, 0, 0); } while (0)
; #define PG8_LDA(dst, b, h) do { _Pragma("unroll") for (int m = 0; m < 4; ++m) _Pragma("unroll") for (int k = 0; k < 2; ++k) dst[m][k] = *(const PG8_LAS bf16x8*)(lds + PG8_SA(b, h) + aoff + m * 2048 + k * 1024); } while (0)
; #define PG8_LDB(dst, b, h) do { _Pragma("unroll") for (int n = 0; n < 2; ++n) _Pragma("unroll") for (int k = 0; k < 2; ++k) dst[n][k] = *(const PG8_LAS bf16x8*)(lds + PG8_SB(b, h) + boff + n * 2048 + k * 1024); } while (0)
; template <class Epi, class Sched, bool ALIGN_EPI = false, bool SP2 = false>
; __device__ __forceinline__ void gemm_phase(PG8_LAS unsigned char* lds, const Gemm g, const Sched& S, const Epi& E) {
;     ...
;         const bool has_next = S.next(ui + 1, nxt);
;         const char* nA = has_next ? (const char*)g.A + (size_t)nxt.pm * tstep : cA; const char* nB = has_next ? (const char*)g.Bt + (size_t)nxt.pn * tstep : cB;
;         for (int t = 0; t < nt; t += 2) {
;             const bool last = (t == nt - 2);
;             const char* a1 = cA + (size_t)(t + 1) * kstep;
;             const char* a2 = last ? nA : cA + (size_t)(t + 2) * kstep; const char* b2 = last ? nB : cB + (size_t)(t + 2) * kstep;
;             const char* a3 = a2 + kstep; const char* b3 = b2 + kstep;
;             if (last && has_next) S.a_ready(nxt);
;             if constexpr (SP2) {
;             PG8_LDB(B0, 0, 0); PG8_LDB(B1, 0, 1); PG8_SCHED; PG8_LDA(At, 0, 0); PG8_STAGE(PG8_SA(1, 1), a1 + hstep, voffA);
;             PG8_WAIT_V(8); PG8_WAIT_L(0); PG8_BAR; PG8_MMA(0, 0, At, B0); PG8_MMA(0, 1, At, B1); PG8_BAR; PG8_SCHED;
;             PG8_LDA(At, 0, 1); PG8_STAGE(PG8_SB(0, 0), b2, voffB); PG8_STAGE(PG8_SB(0, 1), b2 + hstep, voffB); PG8_STAGE(PG8_SA(0, 0), a2, voffA);
;             PG8_WAIT_V(8); PG8_WAIT_L(0); PG8_BAR; PG8_MMA(1, 0, At, B0); PG8_MMA(1, 1, At, B1); PG8_BAR; PG8_SCHED;
;     __device__ __forceinline__ void operator()(const f32x4 (&acc)[2][2][4][2], const pg8::Unit& u, int wr, int wc, int fr, int fq) const {
;     ...
;         for (int ai = 0; ai < 2; ++ai)
; #pragma unroll
;             for (int m = 0; m < 4; ++m) rs8[ai][m] = rstd[256 * pm + 128 * ai + 64 * wr + 16 * m + fr];
.LBB0_410:
	s_lshl_b32 s98, s8, 8
	s_add_i32 s98, s98, s66
	v_add_lshl_u32 v255, v1, s98, 2
	global_load_dword v247, v255, s[16:17]
	global_load_dword v248, v255, s[16:17] offset:64
	global_load_dword v249, v255, s[16:17] offset:128
	global_load_dword v250, v255, s[16:17] offset:192
	global_load_dword v251, v255, s[16:17] offset:512
	global_load_dword v252, v255, s[16:17] offset:576
	global_load_dword v253, v255, s[16:17] offset:640
	global_load_dword v254, v255, s[16:17] offset:704
	s_ashr_i32 s35, s34, 31
	s_lshl_b64 s[0:1], s[34:35], 19
	s_add_u32 s38, s29, s0
	s_addc_u32 s39, s31, s1
	s_and_b64 s[0:1], s[10:11], exec
	s_cselect_b32 s0, s39, s5
	s_cselect_b32 s1, s38, s4
	s_ashr_i32 s37, s36, 31
	s_lshl_b64 s[40:41], s[36:37], 19
	s_add_u32 s40, s48, s40
	s_addc_u32 s41, s49, s41
	s_and_b64 s[44:45], s[10:11], exec
	s_cselect_b32 s9, s41, s7
	s_cselect_b32 s12, s40, s6
	s_add_u32 s4, s4, 0x40080
	s_addc_u32 s5, s5, 0
	s_add_u32 s33, s6, 0x100
	s_addc_u32 s35, s7, 0
	s_mov_b32 s37, -2
	ds_read_b128 v[130:133], v218
	ds_read_b128 v[134:137], v218 offset:1024
	ds_read_b128 v[138:141], v218 offset:2048
	ds_read_b128 v[142:145], v218 offset:3072
	ds_read_b128 v[146:149], v219
	ds_read_b128 v[150:153], v219 offset:1024
	ds_read_b128 v[154:157], v219 offset:2048
	ds_read_b128 v[158:161], v219 offset:3072
	s_add_u32 s6, s4, 0xfffc0080
	s_addc_u32 s7, s5, -1
	s_cmp_eq_u32 s37, 12
	s_cselect_b32 s45, s0, s7
	s_cselect_b32 s44, s1, s6
	s_cselect_b32 s7, s9, s35
	s_cselect_b32 s6, s12, s33
	v_lshl_add_u64 v[226:227], s[4:5], 0, v[188:189]
	s_add_i32 m0, s51, 0xc000
	ds_read_b128 v[162:165], v220
	ds_read_b128 v[166:169], v220 offset:1024
	ds_read_b128 v[170:173], v220 offset:2048
	ds_read_b128 v[196:199], v220 offset:3072
	ds_read_b128 v[200:203], v220 offset:4096
	ds_read_b128 v[204:207], v220 offset:5120
	ds_read_b128 v[208:211], v220 offset:6144
	ds_read_b128 v[212:215], v220 offset:7168
	global_load_lds_dwordx4 v[226:227], off
	v_lshl_add_u64 v[226:227], s[4:5], 0, v[190:191]
	s_add_i32 m0, s51, 0xe000
	s_nop 0
	global_load_lds_dwordx4 v[226:227], off
	s_waitcnt vmcnt(8)
	s_waitcnt lgkmcnt(0)
	s_barrier
	s_setprio 1
	s_waitcnt lgkmcnt(0)
	v_mfma_f32_16x16x32_bf16 v[126:129], v[130:133], v[162:165], 0
	v_mfma_f32_16x16x32_bf16 v[122:125], v[138:141], v[162:165], 0
	v_mfma_f32_16x16x32_bf16 v[110:113], v[130:133], v[170:173], 0
	v_mfma_f32_16x16x32_bf16 v[106:109], v[138:141], v[170:173], 0
	v_mfma_f32_16x16x32_bf16 v[94:97], v[130:133], v[200:203], 0
	v_mfma_f32_16x16x32_bf16 v[90:93], v[138:141], v[200:203], 0
	v_mfma_f32_16x16x32_bf16 v[78:81], v[130:133], v[208:211], 0
	v_mfma_f32_16x16x32_bf16 v[74:77], v[138:141], v[208:211], 0
	v_mfma_f32_16x16x32_bf16 v[126:129], v[134:137], v[166:169], v[126:129]
	v_mfma_f32_16x16x32_bf16 v[122:125], v[142:145], v[166:169], v[122:125]
	v_mfma_f32_16x16x32_bf16 v[110:113], v[134:137], v[196:199], v[110:113]
	v_mfma_f32_16x16x32_bf16 v[106:109], v[142:145], v[196:199], v[106:109]
	v_mfma_f32_16x16x32_bf16 v[94:97], v[134:137], v[204:207], v[94:97]
	v_mfma_f32_16x16x32_bf16 v[90:93], v[142:145], v[204:207], v[90:93]
	v_mfma_f32_16x16x32_bf16 v[78:81], v[134:137], v[212:215], v[78:81]
	v_mfma_f32_16x16x32_bf16 v[74:77], v[142:145], v[212:215], v[74:77]
	s_setprio 0
	s_setprio 1
	v_mfma_f32_16x16x32_bf16 v[118:121], v[146:149], v[162:165], 0
	v_mfma_f32_16x16x32_bf16 v[114:117], v[154:157], v[162:165], 0
	v_mfma_f32_16x16x32_bf16 v[102:105], v[146:149], v[170:173], 0
	v_mfma_f32_16x16x32_bf16 v[98:101], v[154:157], v[170:173], 0
	v_mfma_f32_16x16x32_bf16 v[86:89], v[146:149], v[200:203], 0
	v_mfma_f32_16x16x32_bf16 v[82:85], v[154:157], v[200:203], 0
	v_mfma_f32_16x16x32_bf16 v[70:73], v[146:149], v[208:211], 0
	v_mfma_f32_16x16x32_bf16 v[66:69], v[154:157], v[208:211], 0
	v_mfma_f32_16x16x32_bf16 v[118:121], v[150:153], v[166:169], v[118:121]
	v_mfma_f32_16x16x32_bf16 v[114:117], v[158:161], v[166:169], v[114:117]
	v_mfma_f32_16x16x32_bf16 v[102:105], v[150:153], v[196:199], v[102:105]
	v_mfma_f32_16x16x32_bf16 v[98:101], v[158:161], v[196:199], v[98:101]
	v_mfma_f32_16x16x32_bf16 v[86:89], v[150:153], v[204:207], v[86:89]
	v_mfma_f32_16x16x32_bf16 v[82:85], v[158:161], v[204:207], v[82:85]
	v_mfma_f32_16x16x32_bf16 v[70:73], v[150:153], v[212:215], v[70:73]
	v_mfma_f32_16x16x32_bf16 v[66:69], v[158:161], v[212:215], v[66:69]
	s_setprio 0
	s_barrier
	s_add_i32 s43, s86, s50
	v_lshl_add_u64 v[226:227], s[6:7], 0, v[178:179]
	s_mov_b32 m0, s43
	ds_read_b128 v[162:165], v220 offset:16384
	ds_read_b128 v[166:169], v220 offset:17408
	ds_read_b128 v[170:173], v220 offset:18432
	ds_read_b128 v[196:199], v220 offset:19456
	ds_read_b128 v[200:203], v220 offset:20480
	ds_read_b128 v[204:207], v220 offset:21504
	ds_read_b128 v[208:211], v220 offset:22528
	ds_read_b128 v[212:215], v220 offset:23552
	global_load_lds_dwordx4 v[226:227], off
	s_add_i32 m0, s43, 0x2000
	s_add_u32 s46, s6, 0x40000
	v_lshl_add_u64 v[228:229], s[6:7], 0, v[182:183]
	s_addc_u32 s47, s7, 0
	s_add_i32 s43, s87, s50
	global_load_lds_dwordx4 v[228:229], off
	v_lshl_add_u64 v[230:231], s[46:47], 0, v[178:179]
	s_mov_b32 m0, s43
	v_lshl_add_u64 v[232:233], s[44:45], 0, v[180:181]
	global_load_lds_dwordx4 v[230:231], off
	v_lshl_add_u64 v[230:231], s[46:47], 0, v[182:183]
	s_add_i32 m0, s43, 0x2000
	s_nop 0
	global_load_lds_dwordx4 v[230:231], off
	v_lshl_add_u64 v[230:231], s[44:45], 0, v[176:177]
	s_mov_b32 m0, s51
	s_nop 0
	global_load_lds_dwordx4 v[230:231], off
	s_mov_b32 m0, s52
	s_nop 0
	global_load_lds_dwordx4 v[232:233], off
	s_waitcnt vmcnt(8)
	s_waitcnt lgkmcnt(0)
	s_barrier
; #define PG8_STAGE(bufoff, gbase, voff) do { _Pragma("unroll") for (int _i = 0; _i < 2; ++_i) \
;         __builtin_amdgcn_global_load_lds((const unsigned*)((const char*)(gbase) + (voff)[_i]), (PG8_LAS unsigned*)(lds + (bufoff) + ldsw + _i * 8192), 16, 0, 0); } while (0)
; #define PG8_LDA(dst, b, h) do { _Pragma("unroll") for (int m = 0; m < 4; ++m) _Pragma("unroll") for (int k = 0; k < 2; ++k) dst[m][k] = *(const PG8_LAS bf16x8*)(lds + PG8_SA(b, h) + aoff + m * 2048 + k * 1024); } while (0)
; #define PG8_LDB(dst, b, h) do { _Pragma("unroll") for (int n = 0; n < 2; ++n) _Pragma("unroll") for (int k = 0; k < 2; ++k) dst[n][k] = *(const PG8_LAS bf16x8*)(lds + PG8_SB(b, h) + boff + n * 2048 + k * 1024); } while (0)
; #define PG8_MMA(ai, bj, At, Bt) do { __builtin_amdgcn_s_setprio(1); _Pragma("unroll") for (int m = 0; m < 4; ++m) _Pragma("unroll") for (int n = 0; n < 2; ++n) _Pragma("unroll") for (int k = 0; k < 2; ++k) \
;         acc[ai][bj][m][n] = __builtin_amdgcn_mfma_f32_16x16x32_bf16(Bt[n][k], At[m][k], acc[ai][bj][m][n], 0, 0, 0); __builtin_amdgcn_s_setprio(0); } while (0)
; #define PG8_WAIT_V(n) asm volatile("s_waitcnt vmcnt(" #n ")" ::: "memory")
; #define PG8_WAIT_L(n) asm volatile("s_waitcnt lgkmcnt(" #n ")" ::: "memory")
; #define PG8_BAR __builtin_amdgcn_s_barrier()
; #define PG8_SCHED __builtin_amdgcn_sched_barrier(0)
; template <class Epi, class Sched, bool ALIGN_EPI = false, bool SP2 = false>
; __device__ __forceinline__ void gemm_phase(PG8_LAS unsigned char* lds, const Gemm g, const Sched& S, const Epi& E) {
;     ...
;             PG8_WAIT_V(8); PG8_WAIT_L(0); PG8_BAR; PG8_MMA(1, 0, At, B0); PG8_MMA(1, 1, At, B1); PG8_BAR; PG8_SCHED;
;             PG8_LDB(B0, 1, 0); PG8_LDB(B1, 1, 1); PG8_SCHED; PG8_LDA(At, 1, 0); PG8_STAGE(PG8_SA(0, 1), a2 + hstep, voffA);
;             PG8_WAIT_V(8); PG8_WAIT_L(0); PG8_BAR; PG8_MMA(0, 0, At, B0); PG8_MMA(0, 1, At, B1); PG8_BAR; PG8_SCHED;
	s_setprio 1
	s_waitcnt lgkmcnt(0)
	v_mfma_f32_16x16x32_bf16 v[62:65], v[130:133], v[162:165], 0
	v_mfma_f32_16x16x32_bf16 v[58:61], v[138:141], v[162:165], 0
	v_mfma_f32_16x16x32_bf16 v[46:49], v[130:133], v[170:173], 0
	v_mfma_f32_16x16x32_bf16 v[42:45], v[138:141], v[170:173], 0
	v_mfma_f32_16x16x32_bf16 v[30:33], v[130:133], v[200:203], 0
	v_mfma_f32_16x16x32_bf16 v[26:29], v[138:141], v[200:203], 0
	v_mfma_f32_16x16x32_bf16 v[14:17], v[130:133], v[208:211], 0
	v_mfma_f32_16x16x32_bf16 v[10:13], v[138:141], v[208:211], 0
	v_mfma_f32_16x16x32_bf16 v[62:65], v[134:137], v[166:169], v[62:65]
	v_mfma_f32_16x16x32_bf16 v[58:61], v[142:145], v[166:169], v[58:61]
	v_mfma_f32_16x16x32_bf16 v[46:49], v[134:137], v[196:199], v[46:49]
	v_mfma_f32_16x16x32_bf16 v[42:45], v[142:145], v[196:199], v[42:45]
	v_mfma_f32_16x16x32_bf16 v[30:33], v[134:137], v[204:207], v[30:33]
	v_mfma_f32_16x16x32_bf16 v[26:29], v[142:145], v[204:207], v[26:29]
	v_mfma_f32_16x16x32_bf16 v[14:17], v[134:137], v[212:215], v[14:17]
	v_mfma_f32_16x16x32_bf16 v[10:13], v[142:145], v[212:215], v[10:13]
	s_setprio 0
	s_setprio 1
	v_mfma_f32_16x16x32_bf16 v[54:57], v[146:149], v[162:165], 0
	v_mfma_f32_16x16x32_bf16 v[50:53], v[154:157], v[162:165], 0
	v_mfma_f32_16x16x32_bf16 v[38:41], v[146:149], v[170:173], 0
	v_mfma_f32_16x16x32_bf16 v[34:37], v[154:157], v[170:173], 0
	v_mfma_f32_16x16x32_bf16 v[22:25], v[146:149], v[200:203], 0
	v_mfma_f32_16x16x32_bf16 v[18:21], v[154:157], v[200:203], 0
	v_mfma_f32_16x16x32_bf16 v[6:9], v[146:149], v[208:211], 0
	v_mfma_f32_16x16x32_bf16 v[2:5], v[154:157], v[208:211], 0
	v_mfma_f32_16x16x32_bf16 v[54:57], v[150:153], v[166:169], v[54:57]
	v_mfma_f32_16x16x32_bf16 v[50:53], v[158:161], v[166:169], v[50:53]
	v_mfma_f32_16x16x32_bf16 v[38:41], v[150:153], v[196:199], v[38:41]
	v_mfma_f32_16x16x32_bf16 v[34:37], v[158:161], v[196:199], v[34:37]
	v_mfma_f32_16x16x32_bf16 v[22:25], v[150:153], v[204:207], v[22:25]
	v_mfma_f32_16x16x32_bf16 v[18:21], v[158:161], v[204:207], v[18:21]
	v_mfma_f32_16x16x32_bf16 v[6:9], v[150:153], v[212:215], v[6:9]
	v_mfma_f32_16x16x32_bf16 v[2:5], v[158:161], v[212:215], v[2:5]
	s_setprio 0
	s_barrier
	s_add_i32 s43, 0, 0x18000
	s_add_i32 s46, 0, 0x1c000
	v_add_u32_e32 v142, s43, v217
	v_add_u32_e32 v158, s46, v217
	ds_read_b128 v[130:133], v142
	ds_read_b128 v[134:137], v142 offset:1024
	ds_read_b128 v[138:141], v142 offset:2048
	ds_read_b128 v[142:145], v142 offset:3072
	ds_read_b128 v[146:149], v158
	ds_read_b128 v[150:153], v158 offset:1024
	ds_read_b128 v[154:157], v158 offset:2048
	ds_read_b128 v[158:161], v158 offset:3072
	s_add_u32 s44, s44, 0x40000
	s_addc_u32 s45, s45, 0
	s_mov_b32 m0, s53
	v_lshl_add_u64 v[234:235], s[44:45], 0, v[176:177]
	ds_read_b128 v[162:165], v220 offset:32768
	ds_read_b128 v[166:169], v220 offset:33792
	ds_read_b128 v[170:173], v220 offset:34816
	ds_read_b128 v[196:199], v220 offset:35840
	ds_read_b128 v[200:203], v220 offset:36864
	ds_read_b128 v[204:207], v220 offset:37888
	ds_read_b128 v[208:211], v220 offset:38912
	ds_read_b128 v[212:215], v220 offset:39936
	global_load_lds_dwordx4 v[234:235], off
	v_lshl_add_u64 v[234:235], s[44:45], 0, v[180:181]
	s_mov_b32 m0, s54
	s_nop 0
	global_load_lds_dwordx4 v[234:235], off
	s_waitcnt vmcnt(8)
	s_waitcnt lgkmcnt(0)
	s_barrier
	s_setprio 1
	s_waitcnt lgkmcnt(0)
	v_mfma_f32_16x16x32_bf16 v[126:129], v[130:133], v[162:165], v[126:129]
	v_mfma_f32_16x16x32_bf16 v[122:125], v[138:141], v[162:165], v[122:125]
	v_mfma_f32_16x16x32_bf16 v[110:113], v[130:133], v[170:173], v[110:113]
	v_mfma_f32_16x16x32_bf16 v[106:109], v[138:141], v[170:173], v[106:109]
	v_mfma_f32_16x16x32_bf16 v[94:97], v[130:133], v[200:203], v[94:97]
	v_mfma_f32_16x16x32_bf16 v[90:93], v[138:141], v[200:203], v[90:93]
	v_mfma_f32_16x16x32_bf16 v[78:81], v[130:133], v[208:211], v[78:81]
	v_mfma_f32_16x16x32_bf16 v[74:77], v[138:141], v[208:211], v[74:77]
	v_mfma_f32_16x16x32_bf16 v[126:129], v[134:137], v[166:169], v[126:129]
	v_mfma_f32_16x16x32_bf16 v[122:125], v[142:145], v[166:169], v[122:125]
	v_mfma_f32_16x16x32_bf16 v[110:113], v[134:137], v[196:199], v[110:113]
	v_mfma_f32_16x16x32_bf16 v[106:109], v[142:145], v[196:199], v[106:109]
	v_mfma_f32_16x16x32_bf16 v[94:97], v[134:137], v[204:207], v[94:97]
	v_mfma_f32_16x16x32_bf16 v[90:93], v[142:145], v[204:207], v[90:93]
	v_mfma_f32_16x16x32_bf16 v[78:81], v[134:137], v[212:215], v[78:81]
	v_mfma_f32_16x16x32_bf16 v[74:77], v[142:145], v[212:215], v[74:77]
	s_setprio 0
	s_setprio 1
	v_mfma_f32_16x16x32_bf16 v[118:121], v[146:149], v[162:165], v[118:121]
	v_mfma_f32_16x16x32_bf16 v[114:117], v[154:157], v[162:165], v[114:117]
	v_mfma_f32_16x16x32_bf16 v[102:105], v[146:149], v[170:173], v[102:105]
	v_mfma_f32_16x16x32_bf16 v[98:101], v[154:157], v[170:173], v[98:101]
	v_mfma_f32_16x16x32_bf16 v[86:89], v[146:149], v[200:203], v[86:89]
	v_mfma_f32_16x16x32_bf16 v[82:85], v[154:157], v[200:203], v[82:85]
	v_mfma_f32_16x16x32_bf16 v[70:73], v[146:149], v[208:211], v[70:73]
	v_mfma_f32_16x16x32_bf16 v[66:69], v[154:157], v[208:211], v[66:69]
	v_mfma_f32_16x16x32_bf16 v[118:121], v[150:153], v[166:169], v[118:121]
	v_mfma_f32_16x16x32_bf16 v[114:117], v[158:161], v[166:169], v[114:117]
	v_mfma_f32_16x16x32_bf16 v[102:105], v[150:153], v[196:199], v[102:105]
	v_mfma_f32_16x16x32_bf16 v[98:101], v[158:161], v[196:199], v[98:101]
	v_mfma_f32_16x16x32_bf16 v[86:89], v[150:153], v[204:207], v[86:89]
	v_mfma_f32_16x16x32_bf16 v[82:85], v[158:161], v[204:207], v[82:85]
	v_mfma_f32_16x16x32_bf16 v[70:73], v[150:153], v[212:215], v[70:73]
	v_mfma_f32_16x16x32_bf16 v[66:69], v[158:161], v[212:215], v[66:69]
	s_setprio 0
	s_barrier
; #define PG8_STAGE(bufoff, gbase, voff) do { _Pragma("unroll") for (int _i = 0; _i < 2; ++_i) \
;         __builtin_amdgcn_global_load_lds((const unsigned*)((const char*)(gbase) + (voff)[_i]), (PG8_LAS unsigned*)(lds + (bufoff) + ldsw + _i * 8192), 16, 0, 0); } while (0)
; #define PG8_LDA(dst, b, h) do { _Pragma("unroll") for (int m = 0; m < 4; ++m) _Pragma("unroll") for (int k = 0; k < 2; ++k) dst[m][k] = *(const PG8_LAS bf16x8*)(lds + PG8_SA(b, h) + aoff + m * 2048 + k * 1024); } while (0)
; #define PG8_LDB(dst, b, h) do { _Pragma("unroll") for (int n = 0; n < 2; ++n) _Pragma("unroll") for (int k = 0; k < 2; ++k) dst[n][k] = *(const PG8_LAS bf16x8*)(lds + PG8_SB(b, h) + boff + n * 2048 + k * 1024); } while (0)
; template <class Epi, class Sched, bool ALIGN_EPI = false, bool SP2 = false>
; __device__ __forceinline__ void gemm_phase(PG8_LAS unsigned char* lds, const Gemm g, const Sched& S, const Epi& E) {
;     ...
;         for (int t = 0; t < nt; t += 2) {
;             const bool last = (t == nt - 2);
;             const char* a1 = cA + (size_t)(t + 1) * kstep;
;             const char* a2 = last ? nA : cA + (size_t)(t + 2) * kstep; const char* b2 = last ? nB : cB + (size_t)(t + 2) * kstep;
;             const char* a3 = a2 + kstep; const char* b3 = b2 + kstep;
;             if (last && has_next) S.a_ready(nxt);
;             if constexpr (SP2) {
;             PG8_LDB(B0, 0, 0); PG8_LDB(B1, 0, 1); PG8_SCHED; PG8_LDA(At, 0, 0); PG8_STAGE(PG8_SA(1, 1), a1 + hstep, voffA);
;             PG8_WAIT_V(8); PG8_WAIT_L(0); PG8_BAR; PG8_MMA(0, 0, At, B0); PG8_MMA(0, 1, At, B1); PG8_BAR; PG8_SCHED;
;             PG8_LDA(At, 0, 1); PG8_STAGE(PG8_SB(0, 0), b2, voffB); PG8_STAGE(PG8_SB(0, 1), b2 + hstep, voffB); PG8_STAGE(PG8_SA(0, 0), a2, voffA);
;             PG8_WAIT_V(8); PG8_WAIT_L(0); PG8_BAR; PG8_MMA(1, 0, At, B0); PG8_MMA(1, 1, At, B1); PG8_BAR; PG8_SCHED;
;             PG8_LDB(B0, 1, 0); PG8_LDB(B1, 1, 1); PG8_SCHED; PG8_LDA(At, 1, 0); PG8_STAGE(PG8_SA(0, 1), a2 + hstep, voffA);
;             PG8_WAIT_V(8); PG8_WAIT_L(0); PG8_BAR; PG8_MMA(0, 0, At, B0); PG8_MMA(0, 1, At, B1); PG8_BAR; PG8_SCHED;
;             PG8_LDA(At, 1, 1); PG8_STAGE(PG8_SB(1, 0), b3, voffB); PG8_STAGE(PG8_SB(1, 1), b3 + hstep, voffB); PG8_STAGE(PG8_SA(1, 0), a3, voffA);
;             PG8_WAIT_V(8); PG8_WAIT_L(0); PG8_BAR; PG8_MMA(1, 0, At, B0); PG8_MMA(1, 1, At, B1); PG8_BAR; PG8_SCHED;
	s_add_i32 s43, s43, s50
	v_lshl_add_u64 v[226:227], v[226:227], 0, s[20:21]
	s_mov_b32 m0, s43
	ds_read_b128 v[162:165], v220 offset:49152
	ds_read_b128 v[166:169], v220 offset:50176
	ds_read_b128 v[170:173], v220 offset:51200
	ds_read_b128 v[196:199], v220 offset:52224
	ds_read_b128 v[200:203], v220 offset:53248
	ds_read_b128 v[204:207], v220 offset:54272
	ds_read_b128 v[208:211], v220 offset:55296
	ds_read_b128 v[212:215], v220 offset:56320
	global_load_lds_dwordx4 v[226:227], off
	s_add_i32 m0, s43, 0x2000
	s_add_u32 s6, s6, 0x40080
	v_lshl_add_u64 v[226:227], v[228:229], 0, s[20:21]
	s_addc_u32 s7, s7, 0
	s_add_i32 s43, s46, s50
	global_load_lds_dwordx4 v[226:227], off
	v_lshl_add_u64 v[226:227], s[6:7], 0, v[178:179]
	s_mov_b32 m0, s43
	s_nop 0
	global_load_lds_dwordx4 v[226:227], off
	v_lshl_add_u64 v[226:227], s[6:7], 0, v[182:183]
	s_add_i32 m0, s43, 0x2000
	s_nop 0
	global_load_lds_dwordx4 v[226:227], off
	v_lshl_add_u64 v[226:227], v[230:231], 0, s[20:21]
	s_mov_b32 m0, s67
	s_nop 0
	global_load_lds_dwordx4 v[226:227], off
	v_lshl_add_u64 v[226:227], v[232:233], 0, s[20:21]
	s_mov_b32 m0, s68
	s_nop 0
	global_load_lds_dwordx4 v[226:227], off
	s_waitcnt vmcnt(8)
	s_waitcnt lgkmcnt(0)
	s_barrier
	s_setprio 1
	s_waitcnt lgkmcnt(0)
	v_mfma_f32_16x16x32_bf16 v[62:65], v[130:133], v[162:165], v[62:65]
	v_mfma_f32_16x16x32_bf16 v[58:61], v[138:141], v[162:165], v[58:61]
	v_mfma_f32_16x16x32_bf16 v[46:49], v[130:133], v[170:173], v[46:49]
	v_mfma_f32_16x16x32_bf16 v[42:45], v[138:141], v[170:173], v[42:45]
	v_mfma_f32_16x16x32_bf16 v[30:33], v[130:133], v[200:203], v[30:33]
	v_mfma_f32_16x16x32_bf16 v[26:29], v[138:141], v[200:203], v[26:29]
	v_mfma_f32_16x16x32_bf16 v[14:17], v[130:133], v[208:211], v[14:17]
	v_mfma_f32_16x16x32_bf16 v[10:13], v[138:141], v[208:211], v[10:13]
	v_mfma_f32_16x16x32_bf16 v[62:65], v[134:137], v[166:169], v[62:65]
	v_mfma_f32_16x16x32_bf16 v[58:61], v[142:145], v[166:169], v[58:61]
	v_mfma_f32_16x16x32_bf16 v[46:49], v[134:137], v[196:199], v[46:49]
	v_mfma_f32_16x16x32_bf16 v[42:45], v[142:145], v[196:199], v[42:45]
	v_mfma_f32_16x16x32_bf16 v[30:33], v[134:137], v[204:207], v[30:33]
	v_mfma_f32_16x16x32_bf16 v[26:29], v[142:145], v[204:207], v[26:29]
	v_mfma_f32_16x16x32_bf16 v[14:17], v[134:137], v[212:215], v[14:17]
	v_mfma_f32_16x16x32_bf16 v[10:13], v[142:145], v[212:215], v[10:13]
	s_setprio 0
	s_setprio 1
	v_mfma_f32_16x16x32_bf16 v[54:57], v[146:149], v[162:165], v[54:57]
	v_mfma_f32_16x16x32_bf16 v[50:53], v[154:157], v[162:165], v[50:53]
	v_mfma_f32_16x16x32_bf16 v[38:41], v[146:149], v[170:173], v[38:41]
	v_mfma_f32_16x16x32_bf16 v[34:37], v[154:157], v[170:173], v[34:37]
	v_mfma_f32_16x16x32_bf16 v[22:25], v[146:149], v[200:203], v[22:25]
	v_mfma_f32_16x16x32_bf16 v[18:21], v[154:157], v[200:203], v[18:21]
	v_mfma_f32_16x16x32_bf16 v[6:9], v[146:149], v[208:211], v[6:9]
	v_mfma_f32_16x16x32_bf16 v[2:5], v[154:157], v[208:211], v[2:5]
	v_mfma_f32_16x16x32_bf16 v[54:57], v[150:153], v[166:169], v[54:57]
	v_mfma_f32_16x16x32_bf16 v[50:53], v[158:161], v[166:169], v[50:53]
	v_mfma_f32_16x16x32_bf16 v[38:41], v[150:153], v[196:199], v[38:41]
	v_mfma_f32_16x16x32_bf16 v[34:37], v[158:161], v[196:199], v[34:37]
	v_mfma_f32_16x16x32_bf16 v[22:25], v[150:153], v[204:207], v[22:25]
	v_mfma_f32_16x16x32_bf16 v[18:21], v[158:161], v[204:207], v[18:21]
	v_mfma_f32_16x16x32_bf16 v[6:9], v[150:153], v[212:215], v[6:9]
	v_mfma_f32_16x16x32_bf16 v[2:5], v[158:161], v[212:215], v[2:5]
	s_setprio 0
	s_barrier
	s_add_i32 s37, s37, 2
	s_add_u32 s4, s4, 0x100
	s_addc_u32 s5, s5, 0
	s_add_u32 s33, s33, 0x100
	s_addc_u32 s35, s35, 0
	s_cmp_gt_u32 s37, 13
.LBB0_411:
	ds_read_b128 v[130:133], v218
	ds_read_b128 v[134:137], v218 offset:1024
	ds_read_b128 v[138:141], v218 offset:2048
	ds_read_b128 v[142:145], v218 offset:3072
	ds_read_b128 v[146:149], v219
	ds_read_b128 v[150:153], v219 offset:1024
	ds_read_b128 v[154:157], v219 offset:2048
	ds_read_b128 v[158:161], v219 offset:3072
	s_add_u32 s6, s4, 0xfffc0080
	s_addc_u32 s7, s5, -1
	s_cmp_eq_u32 s37, 12
	s_cselect_b32 s45, s0, s7
	s_cselect_b32 s44, s1, s6
	s_cselect_b32 s7, s9, s35
	s_cselect_b32 s6, s12, s33
	v_lshl_add_u64 v[226:227], s[4:5], 0, v[188:189]
	s_add_i32 m0, s51, 0xc000
	ds_read_b128 v[162:165], v220
	ds_read_b128 v[166:169], v220 offset:1024
	ds_read_b128 v[170:173], v220 offset:2048
	ds_read_b128 v[196:199], v220 offset:3072
	ds_read_b128 v[200:203], v220 offset:4096
	ds_read_b128 v[204:207], v220 offset:5120
	ds_read_b128 v[208:211], v220 offset:6144
	ds_read_b128 v[212:215], v220 offset:7168
	global_load_lds_dwordx4 v[226:227], off
	v_lshl_add_u64 v[226:227], s[4:5], 0, v[190:191]
	s_add_i32 m0, s51, 0xe000
	s_nop 0
	global_load_lds_dwordx4 v[226:227], off
	s_waitcnt vmcnt(8)
	s_waitcnt lgkmcnt(0)
	s_barrier
; #define PG8_STAGE(bufoff, gbase, voff) do { _Pragma("unroll") for (int _i = 0; _i < 2; ++_i) \
;         __builtin_amdgcn_global_load_lds((const unsigned*)((const char*)(gbase) + (voff)[_i]), (PG8_LAS unsigned*)(lds + (bufoff) + ldsw + _i * 8192), 16, 0, 0); } while (0)
; #define PG8_LDA(dst, b, h) do { _Pragma("unroll") for (int m = 0; m < 4; ++m) _Pragma("unroll") for (int k = 0; k < 2; ++k) dst[m][k] = *(const PG8_LAS bf16x8*)(lds + PG8_SA(b, h) + aoff + m * 2048 + k * 1024); } while (0)
; #define PG8_LDB(dst, b, h) do { _Pragma("unroll") for (int n = 0; n < 2; ++n) _Pragma("unroll") for (int k = 0; k < 2; ++k) dst[n][k] = *(const PG8_LAS bf16x8*)(lds + PG8_SB(b, h) + boff + n * 2048 + k * 1024); } while (0)
; #define PG8_MMA(ai, bj, At, Bt) do { __builtin_amdgcn_s_setprio(1); _Pragma("unroll") for (int m = 0; m < 4; ++m) _Pragma("unroll") for (int n = 0; n < 2; ++n) _Pragma("unroll") for (int k = 0; k < 2; ++k) \
;         acc[ai][bj][m][n] = __builtin_amdgcn_mfma_f32_16x16x32_bf16(Bt[n][k], At[m][k], acc[ai][bj][m][n], 0, 0, 0); __builtin_amdgcn_s_setprio(0); } while (0)
; #define PG8_WAIT_V(n) asm volatile("s_waitcnt vmcnt(" #n ")" ::: "memory")
; #define PG8_WAIT_L(n) asm volatile("s_waitcnt lgkmcnt(" #n ")" ::: "memory")
; #define PG8_BAR __builtin_amdgcn_s_barrier()
; #define PG8_SCHED __builtin_amdgcn_sched_barrier(0)
; template <class Epi, class Sched, bool ALIGN_EPI = false, bool SP2 = false>
; __device__ __forceinline__ void gemm_phase(PG8_LAS unsigned char* lds, const Gemm g, const Sched& S, const Epi& E) {
;     ...
;             PG8_WAIT_V(8); PG8_WAIT_L(0); PG8_BAR; PG8_MMA(0, 0, At, B0); PG8_MMA(0, 1, At, B1); PG8_BAR; PG8_SCHED;
;             PG8_LDA(At, 0, 1); PG8_STAGE(PG8_SB(0, 0), b2, voffB); PG8_STAGE(PG8_SB(0, 1), b2 + hstep, voffB); PG8_STAGE(PG8_SA(0, 0), a2, voffA);
;             PG8_WAIT_V(8); PG8_WAIT_L(0); PG8_BAR; PG8_MMA(1, 0, At, B0); PG8_MMA(1, 1, At, B1); PG8_BAR; PG8_SCHED;
;             PG8_LDB(B0, 1, 0); PG8_LDB(B1, 1, 1); PG8_SCHED; PG8_LDA(At, 1, 0); PG8_STAGE(PG8_SA(0, 1), a2 + hstep, voffA);
;             PG8_WAIT_V(8); PG8_WAIT_L(0); PG8_BAR; PG8_MMA(0, 0, At, B0); PG8_MMA(0, 1, At, B1); PG8_BAR; PG8_SCHED;
	s_setprio 1
	s_waitcnt lgkmcnt(0)
	v_mfma_f32_16x16x32_bf16 v[126:129], v[130:133], v[162:165], v[126:129]
	v_mfma_f32_16x16x32_bf16 v[122:125], v[138:141], v[162:165], v[122:125]
	v_mfma_f32_16x16x32_bf16 v[110:113], v[130:133], v[170:173], v[110:113]
	v_mfma_f32_16x16x32_bf16 v[106:109], v[138:141], v[170:173], v[106:109]
	v_mfma_f32_16x16x32_bf16 v[94:97], v[130:133], v[200:203], v[94:97]
	v_mfma_f32_16x16x32_bf16 v[90:93], v[138:141], v[200:203], v[90:93]
	v_mfma_f32_16x16x32_bf16 v[78:81], v[130:133], v[208:211], v[78:81]
	v_mfma_f32_16x16x32_bf16 v[74:77], v[138:141], v[208:211], v[74:77]
	v_mfma_f32_16x16x32_bf16 v[126:129], v[134:137], v[166:169], v[126:129]
	v_mfma_f32_16x16x32_bf16 v[122:125], v[142:145], v[166:169], v[122:125]
	v_mfma_f32_16x16x32_bf16 v[110:113], v[134:137], v[196:199], v[110:113]
	v_mfma_f32_16x16x32_bf16 v[106:109], v[142:145], v[196:199], v[106:109]
	v_mfma_f32_16x16x32_bf16 v[94:97], v[134:137], v[204:207], v[94:97]
	v_mfma_f32_16x16x32_bf16 v[90:93], v[142:145], v[204:207], v[90:93]
	v_mfma_f32_16x16x32_bf16 v[78:81], v[134:137], v[212:215], v[78:81]
	v_mfma_f32_16x16x32_bf16 v[74:77], v[142:145], v[212:215], v[74:77]
	s_setprio 0
	s_setprio 1
	v_mfma_f32_16x16x32_bf16 v[118:121], v[146:149], v[162:165], v[118:121]
	v_mfma_f32_16x16x32_bf16 v[114:117], v[154:157], v[162:165], v[114:117]
	v_mfma_f32_16x16x32_bf16 v[102:105], v[146:149], v[170:173], v[102:105]
	v_mfma_f32_16x16x32_bf16 v[98:101], v[154:157], v[170:173], v[98:101]
	v_mfma_f32_16x16x32_bf16 v[86:89], v[146:149], v[200:203], v[86:89]
	v_mfma_f32_16x16x32_bf16 v[82:85], v[154:157], v[200:203], v[82:85]
	v_mfma_f32_16x16x32_bf16 v[70:73], v[146:149], v[208:211], v[70:73]
	v_mfma_f32_16x16x32_bf16 v[66:69], v[154:157], v[208:211], v[66:69]
	v_mfma_f32_16x16x32_bf16 v[118:121], v[150:153], v[166:169], v[118:121]
	v_mfma_f32_16x16x32_bf16 v[114:117], v[158:161], v[166:169], v[114:117]
	v_mfma_f32_16x16x32_bf16 v[102:105], v[150:153], v[196:199], v[102:105]
	v_mfma_f32_16x16x32_bf16 v[98:101], v[158:161], v[196:199], v[98:101]
	v_mfma_f32_16x16x32_bf16 v[86:89], v[150:153], v[204:207], v[86:89]
	v_mfma_f32_16x16x32_bf16 v[82:85], v[158:161], v[204:207], v[82:85]
	v_mfma_f32_16x16x32_bf16 v[70:73], v[150:153], v[212:215], v[70:73]
	v_mfma_f32_16x16x32_bf16 v[66:69], v[158:161], v[212:215], v[66:69]
	s_setprio 0
	s_barrier
	s_add_i32 s43, s86, s50
	v_lshl_add_u64 v[226:227], s[6:7], 0, v[178:179]
	s_mov_b32 m0, s43
	ds_read_b128 v[162:165], v220 offset:16384
	ds_read_b128 v[166:169], v220 offset:17408
	ds_read_b128 v[170:173], v220 offset:18432
	ds_read_b128 v[196:199], v220 offset:19456
	ds_read_b128 v[200:203], v220 offset:20480
	ds_read_b128 v[204:207], v220 offset:21504
	ds_read_b128 v[208:211], v220 offset:22528
	ds_read_b128 v[212:215], v220 offset:23552
	global_load_lds_dwordx4 v[226:227], off
	s_add_i32 m0, s43, 0x2000
	s_add_u32 s46, s6, 0x40000
	v_lshl_add_u64 v[228:229], s[6:7], 0, v[182:183]
	s_addc_u32 s47, s7, 0
	s_add_i32 s43, s87, s50
	global_load_lds_dwordx4 v[228:229], off
	v_lshl_add_u64 v[230:231], s[46:47], 0, v[178:179]
	s_mov_b32 m0, s43
	v_lshl_add_u64 v[232:233], s[44:45], 0, v[180:181]
	global_load_lds_dwordx4 v[230:231], off
	v_lshl_add_u64 v[230:231], s[46:47], 0, v[182:183]
	s_add_i32 m0, s43, 0x2000
	s_nop 0
	global_load_lds_dwordx4 v[230:231], off
	v_lshl_add_u64 v[230:231], s[44:45], 0, v[176:177]
	s_mov_b32 m0, s51
	s_nop 0
	global_load_lds_dwordx4 v[230:231], off
	s_mov_b32 m0, s52
	s_nop 0
	global_load_lds_dwordx4 v[232:233], off
	s_waitcnt vmcnt(8)
	s_waitcnt lgkmcnt(0)
	s_barrier
	s_setprio 1
	s_waitcnt lgkmcnt(0)
	v_mfma_f32_16x16x32_bf16 v[62:65], v[130:133], v[162:165], v[62:65]
	v_mfma_f32_16x16x32_bf16 v[58:61], v[138:141], v[162:165], v[58:61]
	v_mfma_f32_16x16x32_bf16 v[46:49], v[130:133], v[170:173], v[46:49]
	v_mfma_f32_16x16x32_bf16 v[42:45], v[138:141], v[170:173], v[42:45]
	v_mfma_f32_16x16x32_bf16 v[30:33], v[130:133], v[200:203], v[30:33]
	v_mfma_f32_16x16x32_bf16 v[26:29], v[138:141], v[200:203], v[26:29]
	v_mfma_f32_16x16x32_bf16 v[14:17], v[130:133], v[208:211], v[14:17]
	v_mfma_f32_16x16x32_bf16 v[10:13], v[138:141], v[208:211], v[10:13]
	v_mfma_f32_16x16x32_bf16 v[62:65], v[134:137], v[166:169], v[62:65]
	v_mfma_f32_16x16x32_bf16 v[58:61], v[142:145], v[166:169], v[58:61]
	v_mfma_f32_16x16x32_bf16 v[46:49], v[134:137], v[196:199], v[46:49]
	v_mfma_f32_16x16x32_bf16 v[42:45], v[142:145], v[196:199], v[42:45]
	v_mfma_f32_16x16x32_bf16 v[30:33], v[134:137], v[204:207], v[30:33]
	v_mfma_f32_16x16x32_bf16 v[26:29], v[142:145], v[204:207], v[26:29]
	v_mfma_f32_16x16x32_bf16 v[14:17], v[134:137], v[212:215], v[14:17]
	v_mfma_f32_16x16x32_bf16 v[10:13], v[142:145], v[212:215], v[10:13]
	s_setprio 0
	s_setprio 1
	v_mfma_f32_16x16x32_bf16 v[54:57], v[146:149], v[162:165], v[54:57]
	v_mfma_f32_16x16x32_bf16 v[50:53], v[154:157], v[162:165], v[50:53]
	v_mfma_f32_16x16x32_bf16 v[38:41], v[146:149], v[170:173], v[38:41]
	v_mfma_f32_16x16x32_bf16 v[34:37], v[154:157], v[170:173], v[34:37]
	v_mfma_f32_16x16x32_bf16 v[22:25], v[146:149], v[200:203], v[22:25]
	v_mfma_f32_16x16x32_bf16 v[18:21], v[154:157], v[200:203], v[18:21]
	v_mfma_f32_16x16x32_bf16 v[6:9], v[146:149], v[208:211], v[6:9]
	v_mfma_f32_16x16x32_bf16 v[2:5], v[154:157], v[208:211], v[2:5]
	v_mfma_f32_16x16x32_bf16 v[54:57], v[150:153], v[166:169], v[54:57]
	v_mfma_f32_16x16x32_bf16 v[50:53], v[158:161], v[166:169], v[50:53]
	v_mfma_f32_16x16x32_bf16 v[38:41], v[150:153], v[196:199], v[38:41]
	v_mfma_f32_16x16x32_bf16 v[34:37], v[158:161], v[196:199], v[34:37]
	v_mfma_f32_16x16x32_bf16 v[22:25], v[150:153], v[204:207], v[22:25]
	v_mfma_f32_16x16x32_bf16 v[18:21], v[158:161], v[204:207], v[18:21]
	v_mfma_f32_16x16x32_bf16 v[6:9], v[150:153], v[212:215], v[6:9]
	v_mfma_f32_16x16x32_bf16 v[2:5], v[158:161], v[212:215], v[2:5]
	s_setprio 0
	s_barrier
; #define PG8_STAGE(bufoff, gbase, voff) do { _Pragma("unroll") for (int _i = 0; _i < 2; ++_i) \
;         __builtin_amdgcn_global_load_lds((const unsigned*)((const char*)(gbase) + (voff)[_i]), (PG8_LAS unsigned*)(lds + (bufoff) + ldsw + _i * 8192), 16, 0, 0); } while (0)
; #define PG8_LDA(dst, b, h) do { _Pragma("unroll") for (int m = 0; m < 4; ++m) _Pragma("unroll") for (int k = 0; k < 2; ++k) dst[m][k] = *(const PG8_LAS bf16x8*)(lds + PG8_SA(b, h) + aoff + m * 2048 + k * 1024); } while (0)
; #define PG8_LDB(dst, b, h) do { _Pragma("unroll") for (int n = 0; n < 2; ++n) _Pragma("unroll") for (int k = 0; k < 2; ++k) dst[n][k] = *(const PG8_LAS bf16x8*)(lds + PG8_SB(b, h) + boff + n * 2048 + k * 1024); } while (0)
; #define PG8_MMA(ai, bj, At, Bt) do { __builtin_amdgcn_s_setprio(1); _Pragma("unroll") for (int m = 0; m < 4; ++m) _Pragma("unroll") for (int n = 0; n < 2; ++n) _Pragma("unroll") for (int k = 0; k < 2; ++k) \
;         acc[ai][bj][m][n] = __builtin_amdgcn_mfma_f32_16x16x32_bf16(Bt[n][k], At[m][k], acc[ai][bj][m][n], 0, 0, 0); __builtin_amdgcn_s_setprio(0); } while (0)
; #define PG8_WAIT_V(n) asm volatile("s_waitcnt vmcnt(" #n ")" ::: "memory")
; #define PG8_WAIT_L(n) asm volatile("s_waitcnt lgkmcnt(" #n ")" ::: "memory")
; #define PG8_BAR __builtin_amdgcn_s_barrier()
; #define PG8_SCHED __builtin_amdgcn_sched_barrier(0)
; template <class Epi, class Sched, bool ALIGN_EPI = false, bool SP2 = false>
; __device__ __forceinline__ void gemm_phase(PG8_LAS unsigned char* lds, const Gemm g, const Sched& S, const Epi& E) {
;     ...
;             PG8_LDB(B0, 1, 0); PG8_LDB(B1, 1, 1); PG8_SCHED; PG8_LDA(At, 1, 0); PG8_STAGE(PG8_SA(0, 1), a2 + hstep, voffA);
;             PG8_WAIT_V(8); PG8_WAIT_L(0); PG8_BAR; PG8_MMA(0, 0, At, B0); PG8_MMA(0, 1, At, B1); PG8_BAR; PG8_SCHED;
	s_add_i32 s43, 0, 0x18000
	s_add_i32 s46, 0, 0x1c000
	v_add_u32_e32 v142, s43, v217
	v_add_u32_e32 v158, s46, v217
	ds_read_b128 v[130:133], v142
	ds_read_b128 v[134:137], v142 offset:1024
	ds_read_b128 v[138:141], v142 offset:2048
	ds_read_b128 v[142:145], v142 offset:3072
	ds_read_b128 v[146:149], v158
	ds_read_b128 v[150:153], v158 offset:1024
	ds_read_b128 v[154:157], v158 offset:2048
	ds_read_b128 v[158:161], v158 offset:3072
	s_add_u32 s44, s44, 0x40000
	s_addc_u32 s45, s45, 0
	s_mov_b32 m0, s53
	v_lshl_add_u64 v[234:235], s[44:45], 0, v[176:177]
	ds_read_b128 v[162:165], v220 offset:32768
	ds_read_b128 v[166:169], v220 offset:33792
	ds_read_b128 v[170:173], v220 offset:34816
	ds_read_b128 v[196:199], v220 offset:35840
	ds_read_b128 v[200:203], v220 offset:36864
	ds_read_b128 v[204:207], v220 offset:37888
	ds_read_b128 v[208:211], v220 offset:38912
	ds_read_b128 v[212:215], v220 offset:39936
	global_load_lds_dwordx4 v[234:235], off
	v_lshl_add_u64 v[234:235], s[44:45], 0, v[180:181]
	s_mov_b32 m0, s54
	s_nop 0
	global_load_lds_dwordx4 v[234:235], off
	s_waitcnt vmcnt(8)
	s_waitcnt lgkmcnt(0)
	s_barrier
	s_setprio 1
	s_waitcnt lgkmcnt(0)
	v_mfma_f32_16x16x32_bf16 v[126:129], v[130:133], v[162:165], v[126:129]
	v_mfma_f32_16x16x32_bf16 v[122:125], v[138:141], v[162:165], v[122:125]
	v_mfma_f32_16x16x32_bf16 v[110:113], v[130:133], v[170:173], v[110:113]
	v_mfma_f32_16x16x32_bf16 v[106:109], v[138:141], v[170:173], v[106:109]
	v_mfma_f32_16x16x32_bf16 v[94:97], v[130:133], v[200:203], v[94:97]
	v_mfma_f32_16x16x32_bf16 v[90:93], v[138:141], v[200:203], v[90:93]
	v_mfma_f32_16x16x32_bf16 v[78:81], v[130:133], v[208:211], v[78:81]
	v_mfma_f32_16x16x32_bf16 v[74:77], v[138:141], v[208:211], v[74:77]
	v_mfma_f32_16x16x32_bf16 v[126:129], v[134:137], v[166:169], v[126:129]
	v_mfma_f32_16x16x32_bf16 v[122:125], v[142:145], v[166:169], v[122:125]
	v_mfma_f32_16x16x32_bf16 v[110:113], v[134:137], v[196:199], v[110:113]
	v_mfma_f32_16x16x32_bf16 v[106:109], v[142:145], v[196:199], v[106:109]
	v_mfma_f32_16x16x32_bf16 v[94:97], v[134:137], v[204:207], v[94:97]
	v_mfma_f32_16x16x32_bf16 v[90:93], v[142:145], v[204:207], v[90:93]
	v_mfma_f32_16x16x32_bf16 v[78:81], v[134:137], v[212:215], v[78:81]
	v_mfma_f32_16x16x32_bf16 v[74:77], v[142:145], v[212:215], v[74:77]
	s_setprio 0
	s_setprio 1
	v_mfma_f32_16x16x32_bf16 v[118:121], v[146:149], v[162:165], v[118:121]
	v_mfma_f32_16x16x32_bf16 v[114:117], v[154:157], v[162:165], v[114:117]
	v_mfma_f32_16x16x32_bf16 v[102:105], v[146:149], v[170:173], v[102:105]
	v_mfma_f32_16x16x32_bf16 v[98:101], v[154:157], v[170:173], v[98:101]
	v_mfma_f32_16x16x32_bf16 v[86:89], v[146:149], v[200:203], v[86:89]
	v_mfma_f32_16x16x32_bf16 v[82:85], v[154:157], v[200:203], v[82:85]
	v_mfma_f32_16x16x32_bf16 v[70:73], v[146:149], v[208:211], v[70:73]
	v_mfma_f32_16x16x32_bf16 v[66:69], v[154:157], v[208:211], v[66:69]
	v_mfma_f32_16x16x32_bf16 v[118:121], v[150:153], v[166:169], v[118:121]
	v_mfma_f32_16x16x32_bf16 v[114:117], v[158:161], v[166:169], v[114:117]
	v_mfma_f32_16x16x32_bf16 v[102:105], v[150:153], v[196:199], v[102:105]
	v_mfma_f32_16x16x32_bf16 v[98:101], v[158:161], v[196:199], v[98:101]
	v_mfma_f32_16x16x32_bf16 v[86:89], v[150:153], v[204:207], v[86:89]
	v_mfma_f32_16x16x32_bf16 v[82:85], v[158:161], v[204:207], v[82:85]
	v_mfma_f32_16x16x32_bf16 v[70:73], v[150:153], v[212:215], v[70:73]
	v_mfma_f32_16x16x32_bf16 v[66:69], v[158:161], v[212:215], v[66:69]
	s_setprio 0
	s_barrier
; #define PG8_STAGE(bufoff, gbase, voff) do { _Pragma("unroll") for (int _i = 0; _i < 2; ++_i) \
;         __builtin_amdgcn_global_load_lds((const unsigned*)((const char*)(gbase) + (voff)[_i]), (PG8_LAS unsigned*)(lds + (bufoff) + ldsw + _i * 8192), 16, 0, 0); } while (0)
; #define PG8_LDA(dst, b, h) do { _Pragma("unroll") for (int m = 0; m < 4; ++m) _Pragma("unroll") for (int k = 0; k < 2; ++k) dst[m][k] = *(const PG8_LAS bf16x8*)(lds + PG8_SA(b, h) + aoff + m * 2048 + k * 1024); } while (0)
; #define PG8_MMA(ai, bj, At, Bt) do { __builtin_amdgcn_s_setprio(1); _Pragma("unroll") for (int m = 0; m < 4; ++m) _Pragma("unroll") for (int n = 0; n < 2; ++n) _Pragma("unroll") for (int k = 0; k < 2; ++k) \
;         acc[ai][bj][m][n] = __builtin_amdgcn_mfma_f32_16x16x32_bf16(Bt[n][k], At[m][k], acc[ai][bj][m][n], 0, 0, 0); __builtin_amdgcn_s_setprio(0); } while (0)
; #define PG8_WAIT_V(n) asm volatile("s_waitcnt vmcnt(" #n ")" ::: "memory")
; #define PG8_WAIT_L(n) asm volatile("s_waitcnt lgkmcnt(" #n ")" ::: "memory")
; #define PG8_BAR __builtin_amdgcn_s_barrier()
; #define PG8_SCHED __builtin_amdgcn_sched_barrier(0)
; template <class Epi, class Sched, bool ALIGN_EPI = false, bool SP2 = false>
; __device__ __forceinline__ void gemm_phase(PG8_LAS unsigned char* lds, const Gemm g, const Sched& S, const Epi& E) {
;     ...
;             PG8_LDA(At, 1, 1); PG8_STAGE(PG8_SB(1, 0), b3, voffB); PG8_STAGE(PG8_SB(1, 1), b3 + hstep, voffB); PG8_STAGE(PG8_SA(1, 0), a3, voffA);
;             PG8_WAIT_V(8); PG8_WAIT_L(0); PG8_BAR; PG8_MMA(1, 0, At, B0); PG8_MMA(1, 1, At, B1); PG8_BAR; PG8_SCHED;
;     ...
;         if constexpr (ALIGN_EPI) { if (wr == 0) PG8_BAR; }
	s_add_i32 s43, s43, s50
	v_lshl_add_u64 v[226:227], v[226:227], 0, s[20:21]
	s_mov_b32 m0, s43
	ds_read_b128 v[162:165], v220 offset:49152
	ds_read_b128 v[166:169], v220 offset:50176
	ds_read_b128 v[170:173], v220 offset:51200
	ds_read_b128 v[196:199], v220 offset:52224
	ds_read_b128 v[200:203], v220 offset:53248
	ds_read_b128 v[204:207], v220 offset:54272
	ds_read_b128 v[208:211], v220 offset:55296
	ds_read_b128 v[212:215], v220 offset:56320
	global_load_lds_dwordx4 v[226:227], off
	s_add_i32 m0, s43, 0x2000
	s_add_u32 s6, s6, 0x40080
	v_lshl_add_u64 v[226:227], v[228:229], 0, s[20:21]
	s_addc_u32 s7, s7, 0
	s_add_i32 s43, s46, s50
	global_load_lds_dwordx4 v[226:227], off
	v_lshl_add_u64 v[226:227], s[6:7], 0, v[178:179]
	s_mov_b32 m0, s43
	s_nop 0
	global_load_lds_dwordx4 v[226:227], off
	v_lshl_add_u64 v[226:227], s[6:7], 0, v[182:183]
	s_add_i32 m0, s43, 0x2000
	s_nop 0
	global_load_lds_dwordx4 v[226:227], off
	v_lshl_add_u64 v[226:227], v[230:231], 0, s[20:21]
	s_mov_b32 m0, s67
	s_nop 0
	global_load_lds_dwordx4 v[226:227], off
	v_lshl_add_u64 v[226:227], v[232:233], 0, s[20:21]
	s_mov_b32 m0, s68
	s_nop 0
	global_load_lds_dwordx4 v[226:227], off
	s_waitcnt vmcnt(8)
	s_waitcnt lgkmcnt(0)
	s_barrier
	s_setprio 1
	s_waitcnt lgkmcnt(0)
	v_mfma_f32_16x16x32_bf16 v[62:65], v[130:133], v[162:165], v[62:65]
	v_mfma_f32_16x16x32_bf16 v[58:61], v[138:141], v[162:165], v[58:61]
	v_mfma_f32_16x16x32_bf16 v[46:49], v[130:133], v[170:173], v[46:49]
	v_mfma_f32_16x16x32_bf16 v[42:45], v[138:141], v[170:173], v[42:45]
	v_mfma_f32_16x16x32_bf16 v[30:33], v[130:133], v[200:203], v[30:33]
	v_mfma_f32_16x16x32_bf16 v[26:29], v[138:141], v[200:203], v[26:29]
	v_mfma_f32_16x16x32_bf16 v[14:17], v[130:133], v[208:211], v[14:17]
	v_mfma_f32_16x16x32_bf16 v[10:13], v[138:141], v[208:211], v[10:13]
	v_mfma_f32_16x16x32_bf16 v[62:65], v[134:137], v[166:169], v[62:65]
	v_mfma_f32_16x16x32_bf16 v[58:61], v[142:145], v[166:169], v[58:61]
	v_mfma_f32_16x16x32_bf16 v[46:49], v[134:137], v[196:199], v[46:49]
	v_mfma_f32_16x16x32_bf16 v[42:45], v[142:145], v[196:199], v[42:45]
	v_mfma_f32_16x16x32_bf16 v[30:33], v[134:137], v[204:207], v[30:33]
	v_mfma_f32_16x16x32_bf16 v[26:29], v[142:145], v[204:207], v[26:29]
	v_mfma_f32_16x16x32_bf16 v[14:17], v[134:137], v[212:215], v[14:17]
	v_mfma_f32_16x16x32_bf16 v[10:13], v[142:145], v[212:215], v[10:13]
	s_setprio 0
	s_setprio 1
	v_mfma_f32_16x16x32_bf16 v[54:57], v[146:149], v[162:165], v[54:57]
	v_mfma_f32_16x16x32_bf16 v[50:53], v[154:157], v[162:165], v[50:53]
	v_mfma_f32_16x16x32_bf16 v[38:41], v[146:149], v[170:173], v[38:41]
	v_mfma_f32_16x16x32_bf16 v[34:37], v[154:157], v[170:173], v[34:37]
	v_mfma_f32_16x16x32_bf16 v[22:25], v[146:149], v[200:203], v[22:25]
	v_mfma_f32_16x16x32_bf16 v[18:21], v[154:157], v[200:203], v[18:21]
	v_mfma_f32_16x16x32_bf16 v[6:9], v[146:149], v[208:211], v[6:9]
	v_mfma_f32_16x16x32_bf16 v[2:5], v[154:157], v[208:211], v[2:5]
	v_mfma_f32_16x16x32_bf16 v[54:57], v[150:153], v[166:169], v[54:57]
	v_mfma_f32_16x16x32_bf16 v[50:53], v[158:161], v[166:169], v[50:53]
	v_mfma_f32_16x16x32_bf16 v[38:41], v[150:153], v[196:199], v[38:41]
	v_mfma_f32_16x16x32_bf16 v[34:37], v[158:161], v[196:199], v[34:37]
	v_mfma_f32_16x16x32_bf16 v[22:25], v[150:153], v[204:207], v[22:25]
	v_mfma_f32_16x16x32_bf16 v[18:21], v[158:161], v[204:207], v[18:21]
	v_mfma_f32_16x16x32_bf16 v[6:9], v[150:153], v[212:215], v[6:9]
	v_mfma_f32_16x16x32_bf16 v[2:5], v[158:161], v[212:215], v[2:5]
	s_setprio 0
	s_barrier
	s_add_i32 s37, s37, 2
	s_add_u32 s4, s4, 0x100
	s_addc_u32 s5, s5, 0
	s_add_u32 s33, s33, 0x100
	s_addc_u32 s35, s35, 0
	s_cmp_gt_u32 s37, 13
	s_cbranch_scc0 .LBB0_411
	s_and_b64 vcc, exec, s[22:23]
	s_cbranch_vccz .LBB0_414
	s_barrier
